# retention-output unit: Q/K tile loads issued as one batch and V tile loads as a second batch (was one round trip per 16-byte load)
# baseline (speedup 1.0000x reference)
.LBB0_195:
	s_or_b64 exec, exec, s[10:11]
	v_readlane_b32 s0, v254, 50
	s_waitcnt lgkmcnt(0)
	s_barrier
	v_mov_b32_e32 v0, s0
	ds_read_b32 v0, v0
	s_movk_i32 s0, 0x1ff
	s_mov_b64 s[10:11], -1
	s_waitcnt lgkmcnt(0)
	v_cmp_lt_i32_e32 vcc, s0, v0
	v_readfirstlane_b32 s71, v0
	s_cbranch_vccnz .LBB0_192
	v_readlane_b32 s12, v254, 25
	v_readlane_b32 s14, v254, 27
	v_readlane_b32 s15, v254, 28
	s_mov_b64 s[64:65], s[14:15]
	s_add_u32 s68, s64, 0xc700000
	s_addc_u32 s69, s65, 0
	s_ashr_i32 s10, s71, 6
	s_bfe_u32 s82, s71, 0x40002
	s_ashr_i32 s11, s10, 31
	s_lshl_b64 s[66:67], s[10:11], 11
	s_lshl_b32 s0, s82, 7
	s_or_b32 s80, s66, s0
	s_mul_i32 s66, s67, 0x2800
	s_mul_hi_u32 s0, s80, 0x2800
	s_and_b32 s81, s71, 3
	s_add_i32 s0, s0, s66
	s_mul_i32 s10, s80, 0x2800
	v_readlane_b32 s13, v254, 26
	s_add_u32 s12, s68, s10
	s_addc_u32 s13, s69, s0
	s_lshl_b32 s0, s81, 8
	s_add_u32 s14, s12, s0
	s_addc_u32 s15, s13, 0
	s_add_u32 s10, s14, 0x1000
	s_addc_u32 s11, s15, 0
	v_lshl_add_u64 v[0:1], s[10:11], 0, v[110:111]
	v_lshl_add_u64 v[0:1], v[0:1], 0, v[112:113]
	global_load_dwordx4 v[218:221], v[0:1], off
	v_add_u32_e32 v52, v77, v95
	v_lshl_add_u64 v[0:1], s[10:11], 0, v[114:115]
	v_lshl_add_u64 v[0:1], v[0:1], 0, v[116:117]
	global_load_dwordx4 v[222:225], v[0:1], off
	v_lshl_add_u64 v[0:1], s[10:11], 0, v[118:119]
	v_lshl_add_u64 v[0:1], v[0:1], 0, v[120:121]
	global_load_dwordx4 v[226:229], v[0:1], off
	v_lshl_add_u64 v[0:1], s[10:11], 0, v[122:123]
	v_lshl_add_u64 v[0:1], v[0:1], 0, v[124:125]
	global_load_dwordx4 v[230:233], v[0:1], off
	s_add_u32 s10, s14, 0x1400
	s_addc_u32 s11, s15, 0
	v_lshl_add_u64 v[0:1], s[10:11], 0, v[110:111]
	v_lshl_add_u64 v[0:1], v[0:1], 0, v[112:113]
	global_load_dwordx4 v[234:237], v[0:1], off
	v_lshl_add_u64 v[0:1], s[10:11], 0, v[114:115]
	v_lshl_add_u64 v[0:1], v[0:1], 0, v[116:117]
	global_load_dwordx4 v[238:241], v[0:1], off
	v_lshl_add_u64 v[0:1], s[10:11], 0, v[118:119]
	v_lshl_add_u64 v[0:1], v[0:1], 0, v[120:121]
	global_load_dwordx4 v[242:245], v[0:1], off
	v_lshl_add_u64 v[0:1], s[10:11], 0, v[122:123]
	v_lshl_add_u64 v[0:1], v[0:1], 0, v[124:125]
	global_load_dwordx4 v[246:249], v[0:1], off
	s_lshl_b32 s10, s81, 9
	s_add_u32 s10, s12, s10
	s_addc_u32 s11, s13, 0
	s_add_u32 s10, s10, 0x1800
	s_addc_u32 s11, s11, 0
	s_movk_i32 s12, 0x2000
	s_waitcnt vmcnt(0) lgkmcnt(0)
	ds_write_b128 v181, v[218:221]
	ds_write_b128 v193, v[222:225]
	ds_write_b128 v194, v[226:229]
	ds_write_b128 v195, v[230:233]
	ds_write_b128 v181, v[234:237] offset:34816
	ds_write_b128 v193, v[238:241] offset:34816
	ds_write_b128 v194, v[242:245] offset:34816
	ds_write_b128 v195, v[246:249] offset:34816
	v_lshl_add_u64 v[250:251], v[78:79], 1, s[10:11]
	v_lshl_add_u64 v[250:251], v[80:81], 1, v[250:251]
	global_load_dwordx4 v[218:221], v[250:251], off
	v_add_co_u32_e32 v250, vcc, s12, v250
	s_nop 1
	v_addc_co_u32_e32 v251, vcc, 0, v251, vcc
	global_load_dwordx4 v[222:225], v[250:251], off offset:2048
	v_lshl_add_u64 v[250:251], v[82:83], 1, s[10:11]
	v_lshl_add_u64 v[250:251], v[84:85], 1, v[250:251]
	global_load_dwordx4 v[226:229], v[250:251], off
	v_add_co_u32_e32 v250, vcc, s12, v250
	s_nop 1
	v_addc_co_u32_e32 v251, vcc, 0, v251, vcc
	global_load_dwordx4 v[230:233], v[250:251], off offset:2048
	v_lshl_add_u64 v[250:251], v[86:87], 1, s[10:11]
	v_lshl_add_u64 v[250:251], v[88:89], 1, v[250:251]
	global_load_dwordx4 v[234:237], v[250:251], off
	v_add_co_u32_e32 v250, vcc, s12, v250
	s_nop 1
	v_addc_co_u32_e32 v251, vcc, 0, v251, vcc
	global_load_dwordx4 v[238:241], v[250:251], off offset:2048
	v_lshl_add_u64 v[250:251], v[90:91], 1, s[10:11]
	v_lshl_add_u64 v[250:251], v[92:93], 1, v[250:251]
	global_load_dwordx4 v[242:245], v[250:251], off
	v_add_co_u32_e32 v250, vcc, s12, v250
	s_nop 1
	v_addc_co_u32_e32 v251, vcc, 0, v251, vcc
	global_load_dwordx4 v[246:249], v[250:251], off offset:2048
	s_waitcnt vmcnt(0)
	v_mov_b32_e32 v0, v218
	v_mov_b32_e32 v1, v219
	v_mov_b32_e32 v2, v220
	v_mov_b32_e32 v3, v221
	v_and_b32_e32 v8, 0xffff, v0
	v_mov_b32_e32 v4, v222
	v_mov_b32_e32 v5, v223
	v_mov_b32_e32 v6, v224
	v_mov_b32_e32 v7, v225
	v_lshrrev_b32_e32 v0, 16, v0
	v_lshl_or_b32 v8, v4, 16, v8
	v_and_or_b32 v0, v4, s59, v0
	ds_write2_b32 v196, v8, v0 offset1:68
	v_and_b32_e32 v0, 0xffff, v1
	v_lshrrev_b32_e32 v1, 16, v1
	v_lshl_or_b32 v0, v5, 16, v0
	v_and_or_b32 v1, v5, s59, v1
	ds_write2_b32 v196, v0, v1 offset0:136 offset1:204
	v_and_b32_e32 v0, 0xffff, v2
	v_lshrrev_b32_e32 v1, 16, v2
	v_lshl_or_b32 v0, v6, 16, v0
	v_and_or_b32 v1, v6, s59, v1
	v_add_u32_e32 v2, 0x400, v196
	ds_write2_b32 v2, v0, v1 offset0:16 offset1:84
	v_and_b32_e32 v0, 0xffff, v3
	v_lshrrev_b32_e32 v1, 16, v3
	v_lshl_or_b32 v0, v7, 16, v0
	v_and_or_b32 v1, v7, s59, v1
	ds_write2_b32 v2, v0, v1 offset0:152 offset1:220
	v_mov_b32_e32 v0, v226
	v_mov_b32_e32 v1, v227
	v_mov_b32_e32 v2, v228
	v_mov_b32_e32 v3, v229
	v_and_b32_e32 v8, 0xffff, v0
	v_mov_b32_e32 v4, v230
	v_mov_b32_e32 v5, v231
	v_mov_b32_e32 v6, v232
	v_mov_b32_e32 v7, v233
	v_lshrrev_b32_e32 v0, 16, v0
	v_lshl_or_b32 v8, v4, 16, v8
	v_and_or_b32 v0, v4, s59, v0
	ds_write2_b32 v197, v8, v0 offset1:68
	v_and_b32_e32 v0, 0xffff, v1
	v_lshrrev_b32_e32 v1, 16, v1
	v_lshl_or_b32 v0, v5, 16, v0
	v_and_or_b32 v1, v5, s59, v1
	ds_write2_b32 v197, v0, v1 offset0:136 offset1:204
	v_and_b32_e32 v0, 0xffff, v2
	v_lshrrev_b32_e32 v1, 16, v2
	v_lshl_or_b32 v0, v6, 16, v0
	v_and_or_b32 v1, v6, s59, v1
	v_add_u32_e32 v2, 0x400, v197
	ds_write2_b32 v2, v0, v1 offset0:16 offset1:84
	v_and_b32_e32 v0, 0xffff, v3
	v_lshrrev_b32_e32 v1, 16, v3
	v_lshl_or_b32 v0, v7, 16, v0
	v_and_or_b32 v1, v7, s59, v1
	ds_write2_b32 v2, v0, v1 offset0:152 offset1:220
	v_mov_b32_e32 v0, v234
	v_mov_b32_e32 v1, v235
	v_mov_b32_e32 v2, v236
	v_mov_b32_e32 v3, v237
	v_and_b32_e32 v8, 0xffff, v0
	v_mov_b32_e32 v4, v238
	v_mov_b32_e32 v5, v239
	v_mov_b32_e32 v6, v240
	v_mov_b32_e32 v7, v241
	v_lshrrev_b32_e32 v0, 16, v0
	v_lshl_or_b32 v8, v4, 16, v8
	v_and_or_b32 v0, v4, s59, v0
	ds_write2_b32 v198, v8, v0 offset1:68
	v_and_b32_e32 v0, 0xffff, v1
	v_lshrrev_b32_e32 v1, 16, v1
	v_lshl_or_b32 v0, v5, 16, v0
	v_and_or_b32 v1, v5, s59, v1
	ds_write2_b32 v198, v0, v1 offset0:136 offset1:204
	v_and_b32_e32 v0, 0xffff, v2
	v_lshrrev_b32_e32 v1, 16, v2
	v_lshl_or_b32 v0, v6, 16, v0
	v_and_or_b32 v1, v6, s59, v1
	v_add_u32_e32 v2, 0x400, v198
	ds_write2_b32 v2, v0, v1 offset0:16 offset1:84
	v_and_b32_e32 v0, 0xffff, v3
	v_lshrrev_b32_e32 v1, 16, v3
	v_lshl_or_b32 v0, v7, 16, v0
	v_and_or_b32 v1, v7, s59, v1
	ds_write2_b32 v2, v0, v1 offset0:152 offset1:220
	v_mov_b32_e32 v0, v242
	v_mov_b32_e32 v1, v243
	v_mov_b32_e32 v2, v244
	v_mov_b32_e32 v3, v245
	v_and_b32_e32 v8, 0xffff, v0
	v_mov_b32_e32 v4, v246
	v_mov_b32_e32 v5, v247
	v_mov_b32_e32 v6, v248
	v_mov_b32_e32 v7, v249
	v_lshrrev_b32_e32 v0, 16, v0
	s_andn2_b64 vcc, exec, s[6:7]
	v_lshl_or_b32 v8, v4, 16, v8
	v_and_or_b32 v0, v4, s59, v0
	ds_write2_b32 v199, v8, v0 offset1:68
	v_and_b32_e32 v0, 0xffff, v1
	v_lshrrev_b32_e32 v1, 16, v1
	v_lshl_or_b32 v0, v5, 16, v0
	v_and_or_b32 v1, v5, s59, v1
	ds_write2_b32 v199, v0, v1 offset0:136 offset1:204
	v_and_b32_e32 v0, 0xffff, v2
	v_lshrrev_b32_e32 v1, 16, v2
	v_lshl_or_b32 v0, v6, 16, v0
	v_and_or_b32 v1, v6, s59, v1
	v_add_u32_e32 v2, 0x400, v199
	ds_write2_b32 v2, v0, v1 offset0:16 offset1:84
	v_and_b32_e32 v0, 0xffff, v3
	v_lshrrev_b32_e32 v1, 16, v3
	v_lshl_or_b32 v0, v7, 16, v0
	v_and_or_b32 v1, v7, s59, v1
	ds_write2_b32 v2, v0, v1 offset0:152 offset1:220
	s_waitcnt lgkmcnt(0)
	s_barrier
	ds_read_b128 v[0:3], v201 offset:34816
	v_cndmask_b32_e64 v4, 0, 1, s[6:7]
	v_cmp_ne_u32_e64 s[10:11], 1, v4
	s_cbranch_vccnz .LBB0_200
	ds_read_b128 v[4:7], v52
	s_waitcnt lgkmcnt(0)
	v_mfma_f32_16x16x32_bf16 v[28:31], v[0:3], v[4:7], 0
	v_cndmask_b32_e64 v4, 0, 1, s[8:9]
	v_cmp_ne_u32_e64 s[12:13], 1, v4
	s_andn2_b64 vcc, exec, s[8:9]
	s_cbranch_vccz .LBB0_201
